# diff attention finalize: the eight sub-layernorm gain loads issued together up front instead of one exposed round trip each
# speedup vs baseline: 1.0024x; 1.0024x over previous
; __device__ __forceinline__ unsigned cvtpk(float lo, float hi) { f32x2 v = {lo, hi}; bf16x2_t b = __builtin_convertvector(v, bf16x2_t); return __builtin_bit_cast(unsigned, b); }
; __device__ __forceinline__ float xsum(float a) { auto rr = __builtin_amdgcn_permlane32_swap(__float_as_uint(a), __float_as_uint(a), false, false); return __uint_as_float(rr[0]) + __uint_as_float(rr[1]); }
; template <int MODE, int NQ>
; __device__ __forceinline__ void attn_unit(LAS unsigned char* lds, const Params& P, int layer, int b, int h, int qb) {
;     ...
;         bf16_t* orow = mix + (rowbase + qpos0) * DM + ocol + 8 * hi;
;         const float lam = __hip_atomic_load((const float*)(P.ws + WS_LAM) + layer, __ATOMIC_RELAXED, __HIP_MEMORY_SCOPE_AGENT);
;         const float lam_init = 0.8f - 0.6f * expf(-0.3f * (float)layer);
;         const float i1 = 1.f / lrun[0], i2 = lam / lrun[NC - 1];
;         float ss = 0.f;
; #pragma unroll
;         for (int d = 0; d < 2; ++d)
; #pragma unroll
;             for (int r = 0; r < 16; ++r) { const float v = o[0][d][r] * i1 - o[NC - 1][d][r] * i2; o[0][d][r] = v; ss += v * v; }
;         ss = xsum(ss);
;         const float sc_ = rsqrtf(ss * (1.0f / 64.0f) + EPS) * (1.f - lam_init);
;         const float* gn = P.a_subln + layer * 64 + 4 * hi;
; #pragma unroll
;         for (int d = 0; d < 2; ++d)
; #pragma unroll
;             for (int gp = 0; gp < 2; ++gp) {
;                 u32x2 ab[2];
; #pragma unroll
;                 for (int e = 0; e < 2; ++e) { const int g = 2 * gp + e;
;                     const f32x4 gv = *(const f32x4*)(gn + 32 * d + 8 * g);
;                     ab[e].x = cvtpk(o[0][d][4 * g] * sc_ * gv[0], o[0][d][4 * g + 1] * sc_ * gv[1]); ab[e].y = cvtpk(o[0][d][4 * g + 2] * sc_ * gv[2], o[0][d][4 * g + 3] * sc_ * gv[3]); }
.LBB0_394:
	s_barrier
	s_setprio 0
	global_load_dword v0, v1, s[44:45] sc1
	v_div_scale_f32 v4, s[0:1], v188, v188, 1.0
	v_rcp_f32_e32 v5, v4
	v_lshlrev_b64 v[2:3], 11, v[176:177]
	v_lshl_add_u64 v[2:3], s[12:13], 0, v[2:3]
	s_lshl_b32 s72, s4, 1
	v_fma_f32 v6, -v4, v5, 1.0
	v_fmac_f32_e32 v5, v6, v5
	v_div_scale_f32 v6, vcc, 1.0, v188, 1.0
	v_mul_f32_e32 v7, v6, v5
	v_fma_f32 v8, -v4, v7, v6
	v_fmac_f32_e32 v7, v8, v5
	v_fma_f32 v4, -v4, v7, v6
	v_div_fmas_f32 v4, v4, v5, v7
	v_div_fixup_f32 v80, v4, v188, 1.0
	v_lshl_add_u64 v[2:3], v[2:3], 0, s[72:73]
	v_lshlrev_b32_e32 v81, 2, v185
	s_add_i32 s21, s21, s86
	s_add_i32 s20, s20, 1
	s_cmpk_lt_i32 s21, 0x200
	s_waitcnt vmcnt(0)
	v_div_scale_f32 v4, s[0:1], v187, v187, v0
	v_rcp_f32_e32 v5, v4
	s_nop 0
	v_fma_f32 v6, -v4, v5, 1.0
	v_fmac_f32_e32 v5, v6, v5
	v_div_scale_f32 v6, vcc, v0, v187, v0
	v_mul_f32_e32 v7, v6, v5
	v_fma_f32 v8, -v4, v7, v6
	v_fmac_f32_e32 v7, v8, v5
	v_fma_f32 v4, -v4, v7, v6
	v_div_fmas_f32 v4, v4, v5, v7
	v_div_fixup_f32 v82, v4, v187, v0
	v_lshlrev_b32_e32 v0, 1, v186
	v_lshl_add_u64 v[10:11], v[2:3], 0, v[0:1]
	global_load_dwordx4 v[6:9], v81, s[46:47]
	global_load_dwordx4 v[2:5], v81, s[46:47] offset:32
	global_load_dwordx4 v[128:131], v81, s[46:47] offset:64
	global_load_dwordx4 v[132:135], v81, s[46:47] offset:96
	global_load_dwordx4 v[136:139], v81, s[46:47] offset:128
	global_load_dwordx4 v[140:143], v81, s[46:47] offset:160
	global_load_dwordx4 v[144:147], v81, s[46:47] offset:192
	global_load_dwordx4 v[148:151], v81, s[46:47] offset:224
	v_pk_mul_f32 v[14:15], v[52:53], v[82:83] op_sel_hi:[1,0]
	v_pk_mul_f32 v[12:13], v[54:55], v[82:83] op_sel_hi:[1,0]
	v_pk_fma_f32 v[52:53], v[80:81], v[68:69], v[14:15] op_sel_hi:[0,1,1] neg_lo:[0,0,1] neg_hi:[0,0,1]
	v_pk_mul_f32 v[14:15], v[50:51], v[82:83] op_sel_hi:[1,0]
	v_pk_fma_f32 v[12:13], v[80:81], v[70:71], v[12:13] op_sel_hi:[0,1,1] neg_lo:[0,0,1] neg_hi:[0,0,1]
	v_pk_fma_f32 v[50:51], v[80:81], v[66:67], v[14:15] op_sel_hi:[0,1,1] neg_lo:[0,0,1] neg_hi:[0,0,1]
	v_pk_mul_f32 v[14:15], v[48:49], v[82:83] op_sel_hi:[1,0]
	v_pk_mul_f32 v[56:57], v[56:57], v[82:83] op_sel_hi:[1,0]
	v_pk_fma_f32 v[54:55], v[80:81], v[64:65], v[14:15] op_sel_hi:[0,1,1] neg_lo:[0,0,1] neg_hi:[0,0,1]
	v_mul_f32_e32 v0, v55, v55
	v_pk_fma_f32 v[14:15], v[54:55], v[54:55], v[0:1] op_sel_hi:[1,1,0]
	v_mul_f32_e32 v0, v51, v51
	v_pk_fma_f32 v[14:15], v[50:51], v[50:51], v[14:15]
	v_pk_fma_f32 v[56:57], v[80:81], v[72:73], v[56:57] op_sel_hi:[0,1,1] neg_lo:[0,0,1] neg_hi:[0,0,1]
	v_pk_add_f32 v[14:15], v[0:1], v[14:15] op_sel_hi:[0,1]
	v_pk_fma_f32 v[14:15], v[52:53], v[52:53], v[14:15]
	v_mul_f32_e32 v0, v53, v53
	v_pk_add_f32 v[14:15], v[0:1], v[14:15] op_sel_hi:[0,1]
	v_pk_fma_f32 v[14:15], v[12:13], v[12:13], v[14:15]
	v_mul_f32_e32 v0, v13, v13
	v_pk_add_f32 v[64:65], v[0:1], v[14:15] op_sel_hi:[0,1]
	v_pk_mul_f32 v[48:49], v[60:61], v[82:83] op_sel_hi:[1,0]
	v_pk_mul_f32 v[58:59], v[58:59], v[82:83] op_sel_hi:[1,0]
	v_pk_fma_f32 v[60:61], v[56:57], v[56:57], v[64:65]
	v_mul_f32_e32 v0, v57, v57
	v_pk_fma_f32 v[58:59], v[80:81], v[74:75], v[58:59] op_sel_hi:[0,1,1] neg_lo:[0,0,1] neg_hi:[0,0,1]
	v_pk_add_f32 v[60:61], v[0:1], v[60:61] op_sel_hi:[0,1]
	v_pk_fma_f32 v[60:61], v[58:59], v[58:59], v[60:61]
	v_mul_f32_e32 v0, v59, v59
	v_pk_fma_f32 v[48:49], v[80:81], v[76:77], v[48:49] op_sel_hi:[0,1,1] neg_lo:[0,0,1] neg_hi:[0,0,1]
	v_pk_add_f32 v[60:61], v[0:1], v[60:61] op_sel_hi:[0,1]
	v_pk_mul_f32 v[14:15], v[62:63], v[82:83] op_sel_hi:[1,0]
	v_pk_fma_f32 v[60:61], v[48:49], v[48:49], v[60:61]
	v_mul_f32_e32 v0, v49, v49
	v_pk_fma_f32 v[14:15], v[80:81], v[78:79], v[14:15] op_sel_hi:[0,1,1] neg_lo:[0,0,1] neg_hi:[0,0,1]
	v_pk_add_f32 v[60:61], v[0:1], v[60:61] op_sel_hi:[0,1]
	v_pk_mul_f32 v[34:35], v[34:35], v[82:83] op_sel_hi:[1,0]
	v_pk_fma_f32 v[60:61], v[14:15], v[14:15], v[60:61]
	v_mul_f32_e32 v0, v15, v15
	v_pk_fma_f32 v[34:35], v[80:81], v[18:19], v[34:35] op_sel_hi:[0,1,1] neg_lo:[0,0,1] neg_hi:[0,0,1]
	v_pk_mul_f32 v[18:19], v[32:33], v[82:83] op_sel_hi:[1,0]
	v_pk_add_f32 v[60:61], v[0:1], v[60:61] op_sel_hi:[0,1]
	v_pk_fma_f32 v[32:33], v[80:81], v[16:17], v[18:19] op_sel_hi:[0,1,1] neg_lo:[0,0,1] neg_hi:[0,0,1]
	v_pk_fma_f32 v[16:17], v[32:33], v[32:33], v[60:61]
	v_mul_f32_e32 v0, v33, v33
	v_pk_add_f32 v[16:17], v[0:1], v[16:17] op_sel_hi:[0,1]
	v_pk_mul_f32 v[36:37], v[36:37], v[82:83] op_sel_hi:[1,0]
	v_pk_fma_f32 v[16:17], v[34:35], v[34:35], v[16:17]
	v_mul_f32_e32 v0, v35, v35
	v_pk_fma_f32 v[20:21], v[80:81], v[20:21], v[36:37] op_sel_hi:[0,1,1] neg_lo:[0,0,1] neg_hi:[0,0,1]
	v_pk_add_f32 v[16:17], v[0:1], v[16:17] op_sel_hi:[0,1]
	v_pk_mul_f32 v[38:39], v[38:39], v[82:83] op_sel_hi:[1,0]
	v_pk_fma_f32 v[16:17], v[20:21], v[20:21], v[16:17]
	v_mul_f32_e32 v0, v21, v21
	v_pk_mul_f32 v[18:19], v[44:45], v[82:83] op_sel_hi:[1,0]
	v_pk_fma_f32 v[22:23], v[80:81], v[22:23], v[38:39] op_sel_hi:[0,1,1] neg_lo:[0,0,1] neg_hi:[0,0,1]
	v_pk_add_f32 v[16:17], v[0:1], v[16:17] op_sel_hi:[0,1]
	v_pk_fma_f32 v[18:19], v[80:81], v[28:29], v[18:19] op_sel_hi:[0,1,1] neg_lo:[0,0,1] neg_hi:[0,0,1]
	v_pk_mul_f32 v[28:29], v[42:43], v[82:83] op_sel_hi:[1,0]
	v_pk_fma_f32 v[16:17], v[22:23], v[22:23], v[16:17]
	v_mul_f32_e32 v0, v23, v23
	v_pk_fma_f32 v[26:27], v[80:81], v[26:27], v[28:29] op_sel_hi:[0,1,1] neg_lo:[0,0,1] neg_hi:[0,0,1]
	v_pk_mul_f32 v[28:29], v[40:41], v[82:83] op_sel_hi:[1,0]
	v_pk_add_f32 v[36:37], v[0:1], v[16:17] op_sel_hi:[0,1]
	v_pk_fma_f32 v[24:25], v[80:81], v[24:25], v[28:29] op_sel_hi:[0,1,1] neg_lo:[0,0,1] neg_hi:[0,0,1]
	v_pk_fma_f32 v[28:29], v[24:25], v[24:25], v[36:37]
	v_mul_f32_e32 v0, v25, v25
	v_pk_add_f32 v[28:29], v[0:1], v[28:29] op_sel_hi:[0,1]
	v_pk_fma_f32 v[28:29], v[26:27], v[26:27], v[28:29]
	v_mul_f32_e32 v0, v27, v27
	v_pk_add_f32 v[28:29], v[0:1], v[28:29] op_sel_hi:[0,1]
	v_pk_mul_f32 v[16:17], v[46:47], v[82:83] op_sel_hi:[1,0]
	v_pk_fma_f32 v[28:29], v[18:19], v[18:19], v[28:29]
	v_mul_f32_e32 v0, v19, v19
	v_pk_fma_f32 v[16:17], v[80:81], v[30:31], v[16:17] op_sel_hi:[0,1,1] neg_lo:[0,0,1] neg_hi:[0,0,1]
	v_pk_add_f32 v[28:29], v[0:1], v[28:29] op_sel_hi:[0,1]
	v_pk_fma_f32 v[28:29], v[16:17], v[16:17], v[28:29]
	v_mul_f32_e32 v0, v17, v17
	v_pk_add_f32 v[28:29], v[0:1], v[28:29] op_sel_hi:[0,1]
	v_mov_b32_e32 v0, v28
	s_nop 1
	v_permlane32_swap_b32_e32 v28, v0
	v_add_f32_e32 v0, v28, v0
	v_fmamk_f32 v0, v0, 0x3c800000, v212
	v_cmp_gt_f32_e32 vcc, s69, v0
	v_mul_f32_e32 v28, 0x4b800000, v0
	s_nop 0
	v_cndmask_b32_e32 v0, v0, v28, vcc
	v_rsq_f32_e32 v0, v0
	s_nop 0
	v_mul_f32_e32 v28, 0x45800000, v0
	v_cndmask_b32_e32 v0, v0, v28, vcc
	v_mul_f32_e32 v0, v184, v0
	v_pk_mul_f32 v[28:29], v[54:55], v[0:1] op_sel_hi:[1,0]
	s_waitcnt vmcnt(7)
; __device__ __forceinline__ unsigned cvtpk(float lo, float hi) { f32x2 v = {lo, hi}; bf16x2_t b = __builtin_convertvector(v, bf16x2_t); return __builtin_bit_cast(unsigned, b); }
; template <int MODE, int NQ>
; __device__ __forceinline__ void attn_unit(LAS unsigned char* lds, const Params& P, int layer, int b, int h, int qb) {
;     ...
; #pragma unroll
;         for (int d = 0; d < 2; ++d)
; #pragma unroll
;             for (int gp = 0; gp < 2; ++gp) {
;                 u32x2 ab[2];
; #pragma unroll
;                 for (int e = 0; e < 2; ++e) { const int g = 2 * gp + e;
;                     const f32x4 gv = *(const f32x4*)(gn + 32 * d + 8 * g);
;                     ab[e].x = cvtpk(o[0][d][4 * g] * sc_ * gv[0], o[0][d][4 * g + 1] * sc_ * gv[1]); ab[e].y = cvtpk(o[0][d][4 * g + 2] * sc_ * gv[2], o[0][d][4 * g + 3] * sc_ * gv[3]); }
;                 *(u32x4*)(orow + 32 * d + 16 * gp) = pair_swap(ab[0], ab[1]);
;             }
	v_pk_mul_f32 v[6:7], v[6:7], v[28:29]
	v_pk_mul_f32 v[28:29], v[50:51], v[0:1] op_sel_hi:[1,0]
	v_cvt_pk_bf16_f32 v6, v6, v7
	v_pk_mul_f32 v[8:9], v[8:9], v[28:29]
	s_nop 0
	v_cvt_pk_bf16_f32 v7, v8, v9
	v_pk_mul_f32 v[8:9], v[52:53], v[0:1] op_sel_hi:[1,0]
	s_waitcnt vmcnt(0)
	v_pk_mul_f32 v[2:3], v[2:3], v[8:9]
	s_nop 0
	v_cvt_pk_bf16_f32 v8, v2, v3
	v_pk_mul_f32 v[2:3], v[12:13], v[0:1] op_sel_hi:[1,0]
	s_nop 0
	v_permlane32_swap_b32_e32 v6, v8
	v_pk_mul_f32 v[2:3], v[4:5], v[2:3]
	s_nop 0
	v_cvt_pk_bf16_f32 v9, v2, v3
	s_nop 1
	v_permlane32_swap_b32_e32 v7, v9
	global_store_dwordx4 v[10:11], v[6:9], off
	s_nop 1
	v_mov_b64_e32 v[2:3], v[128:129]
	v_mov_b64_e32 v[4:5], v[130:131]
	s_nop 0
	v_pk_mul_f32 v[6:7], v[56:57], v[0:1] op_sel_hi:[1,0]
	v_pk_mul_f32 v[8:9], v[48:49], v[0:1] op_sel_hi:[1,0]
	s_nop 0
	v_pk_mul_f32 v[2:3], v[2:3], v[6:7]
	v_pk_mul_f32 v[6:7], v[58:59], v[0:1] op_sel_hi:[1,0]
	v_cvt_pk_bf16_f32 v2, v2, v3
	v_pk_mul_f32 v[4:5], v[4:5], v[6:7]
	s_nop 0
	v_cvt_pk_bf16_f32 v3, v4, v5
	s_nop 1
	v_mov_b64_e32 v[4:5], v[132:133]
	v_mov_b64_e32 v[6:7], v[134:135]
	s_nop 0
	v_pk_mul_f32 v[4:5], v[4:5], v[8:9]
	v_pk_mul_f32 v[8:9], v[14:15], v[0:1] op_sel_hi:[1,0]
	v_cvt_pk_bf16_f32 v4, v4, v5
	v_pk_mul_f32 v[6:7], v[6:7], v[8:9]
	s_nop 0
	v_permlane32_swap_b32_e32 v2, v4
	v_cvt_pk_bf16_f32 v5, v6, v7
	s_nop 1
	v_permlane32_swap_b32_e32 v3, v5
	global_store_dwordx4 v[10:11], v[2:5], off offset:32
	s_nop 1
	v_mov_b64_e32 v[2:3], v[136:137]
	v_mov_b64_e32 v[4:5], v[138:139]
	v_pk_mul_f32 v[6:7], v[32:33], v[0:1] op_sel_hi:[1,0]
	v_pk_mul_f32 v[8:9], v[20:21], v[0:1] op_sel_hi:[1,0]
	s_nop 0
	v_pk_mul_f32 v[2:3], v[2:3], v[6:7]
	v_pk_mul_f32 v[6:7], v[34:35], v[0:1] op_sel_hi:[1,0]
	v_cvt_pk_bf16_f32 v2, v2, v3
	v_pk_mul_f32 v[4:5], v[4:5], v[6:7]
	s_nop 0
	v_cvt_pk_bf16_f32 v3, v4, v5
	s_nop 1
	v_mov_b64_e32 v[4:5], v[140:141]
	v_mov_b64_e32 v[6:7], v[142:143]
	s_nop 0
	v_pk_mul_f32 v[4:5], v[8:9], v[4:5]
	v_pk_mul_f32 v[8:9], v[22:23], v[0:1] op_sel_hi:[1,0]
	v_cvt_pk_bf16_f32 v4, v4, v5
	v_pk_mul_f32 v[6:7], v[8:9], v[6:7]
	s_nop 0
	v_permlane32_swap_b32_e32 v2, v4
	v_cvt_pk_bf16_f32 v5, v6, v7
	s_nop 1
	v_permlane32_swap_b32_e32 v3, v5
	global_store_dwordx4 v[10:11], v[2:5], off offset:64
	s_nop 1
	v_mov_b64_e32 v[2:3], v[144:145]
	v_mov_b64_e32 v[4:5], v[146:147]
	v_pk_mul_f32 v[6:7], v[24:25], v[0:1] op_sel_hi:[1,0]
	v_pk_mul_f32 v[8:9], v[18:19], v[0:1] op_sel_hi:[1,0]
	s_nop 0
	v_pk_mul_f32 v[2:3], v[6:7], v[2:3]
	v_pk_mul_f32 v[6:7], v[26:27], v[0:1] op_sel_hi:[1,0]
	v_cvt_pk_bf16_f32 v2, v2, v3
	v_pk_mul_f32 v[4:5], v[6:7], v[4:5]
	s_nop 0
	v_cvt_pk_bf16_f32 v3, v4, v5
	s_nop 1
	v_mov_b64_e32 v[4:5], v[148:149]
	v_mov_b64_e32 v[6:7], v[150:151]
	s_nop 0
	v_pk_mul_f32 v[4:5], v[8:9], v[4:5]
	v_pk_mul_f32 v[8:9], v[16:17], v[0:1] op_sel_hi:[1,0]
	v_cvt_pk_bf16_f32 v4, v4, v5
	v_pk_mul_f32 v[6:7], v[8:9], v[6:7]
	s_nop 0
	v_permlane32_swap_b32_e32 v2, v4
	v_cvt_pk_bf16_f32 v5, v6, v7
	s_nop 1
	v_permlane32_swap_b32_e32 v3, v5
	global_store_dwordx4 v[10:11], v[2:5], off offset:96
	s_cbranch_scc0 .LBB0_482
